# GEMM1 column rotation table 0x1f240: chosen as the min-max over several epilogue cost models after the packed gelu/silu rewrite (ZT tiles treated as cheap)
# speedup vs baseline: 1.0038x; 1.0038x over previous
.LBB0_263:
	s_add_i32 s58, s58, 1
	s_mul_i32 s0, s58, s31
	s_mul_hi_u32 s1, s58, s3
	s_add_i32 s1, s1, s0
	s_mul_i32 s0, s58, s3
	s_add_u32 s14, s0, s2
	s_addc_u32 s15, s1, s7
	v_mov_b64_e32 v[2:3], 0x900
	v_cmp_lt_i64_e64 s[40:41], s[14:15], v[2:3]
	v_mov_b64_e32 v[2:3], 0x8ff
	v_cmp_gt_i64_e32 vcc, s[14:15], v[2:3]
	s_cbranch_vccnz .LBB0_265
	s_ashr_i32 s0, s14, 31
	s_lshr_b32 s0, s0, 29
	s_add_i32 s0, s14, s0
	s_ashr_i32 s1, s0, 3
	s_and_b32 s0, s0, -8
	s_sub_i32 s0, s14, s0
	s_cmp_lt_i32 s0, 0
	s_cselect_b32 s14, s83, 0x120
	s_mul_i32 s0, s0, s14
	s_add_i32 s0, s0, s1
	s_mul_hi_i32 s1, s0, 0x2aaaaaab
	s_lshr_b32 s14, s1, 31
	s_ashr_i32 s1, s1, 4
	s_add_i32 s1, s1, s14
	s_lshl_b32 s14, s1, 3
	s_sub_i32 s15, 0xc0, s14
	s_min_i32 s15, s15, 8
	s_abs_i32 s16, s15
	v_cvt_f32_u32_e32 v2, s16
	s_sub_i32 s35, 0, s16
	s_mulk_i32 s1, 0x60
	s_sub_i32 s0, s0, s1
	v_rcp_iflag_f32_e32 v2, v2
	s_abs_i32 s1, s0
	s_xor_b32 s17, s0, s15
	s_ashr_i32 s17, s17, 31
	v_mul_f32_e32 v2, 0x4f7ffffe, v2
	v_cvt_u32_f32_e32 v2, v2
	s_nop 0
	v_readfirstlane_b32 s38, v2
	s_mul_i32 s35, s35, s38
	s_mul_hi_u32 s35, s38, s35
	s_add_i32 s38, s38, s35
	s_mul_hi_u32 s35, s1, s38
	s_mul_i32 s38, s35, s16
	s_sub_i32 s1, s1, s38
	s_add_i32 s39, s35, 1
	s_sub_i32 s38, s1, s16
	s_cmp_ge_u32 s1, s16
	s_cselect_b32 s35, s39, s35
	s_cselect_b32 s1, s38, s1
	s_add_i32 s38, s35, 1
	s_cmp_ge_u32 s1, s16
	s_cselect_b32 s1, s38, s35
	s_xor_b32 s1, s1, s17
	s_sub_i32 s48, s1, s17
	s_mul_i32 s1, s48, s15
	s_sub_i32 s0, s0, s1
	s_add_i32 s50, s14, s0
	s_lshl_b32 s1, s58, 1
	s_lshr_b32 s1, 0x1f240, s1
	s_add_i32 s1, s1, s48
	s_and_b32 s1, s1, 3
	s_and_b32 s48, s48, -4
	s_or_b32 s48, s48, s1
